# NSA gate scalars loaded in one batch; P6 row loop: spurious vmcnt waits dropped, rope table rows prefetched one iteration ahead
# speedup vs baseline: 1.0014x; 1.0014x over previous
; #define LAS __attribute__((address_space(3)))
; __global__ void __launch_bounds__(NTHREADS, 2) mega_fwd(Args a_unused) {
;     ...
;         LAS v4u* rb = (LAS v4u*)(lds + wave * 4096); LAS unsigned short* hb = (LAS unsigned short*)rb;
;         float gq[6], gk[4];
; #pragma unroll
;         for (int j = 0; j < 3; ++j) { gq[2 * j] = ap->in[16][2 * lane + 128 * j]; gq[2 * j + 1] = ap->in[16][2 * lane + 128 * j + 1]; }
; #pragma unroll
;         for (int j = 0; j < 2; ++j) { gk[2 * j] = ap->in[17][2 * lane + 128 * j]; gk[2 * j + 1] = ap->in[17][2 * lane + 128 * j + 1]; }
;         v4u hv[4];
;         if (gw < M) {
; #pragma unroll
;             for (int j = 0; j < 4; ++j) hv[j] = ((const v4u*)(H + (size_t)gw * DINP))[lane + 64 * j];
;         }
;         for (int m = gw; m < M; m += NGW) {
;             const int b = m >> 13, t = m & 8191;
;             f32x4 c8[4];
; #pragma unroll
;             for (int j = 0; j < 4; ++j) c8[j] = *(const f32x4*)(CS8 + t * 16 + 4 * j);
;             const float c16 = CS16[t * 32 + (lane & 15)], s16 = CS16[t * 32 + 16 + (lane & 15)];
.LBB0_566:
	s_or_b64 exec, exec, s[6:7]
	s_mov_b64 s[6:7], s[0:1]
	s_waitcnt lgkmcnt(0)
	s_barrier
	v_readfirstlane_b32 s8, v144
	v_mov_b64_e32 v[0:1], s[6:7]
	global_load_dwordx2 v[0:1], v[0:1], off offset:200
	s_lshr_b32 s8, s8, 6
	s_add_i32 s18, s8, s3
	v_lshrrev_b32_e32 v160, 3, v144
	v_and_b32_e32 v168, 15, v144
	s_cmpk_lt_i32 s18, 0x4000
	v_lshlrev_b32_e32 v128, 1, v141
	s_waitcnt vmcnt(0) lgkmcnt(0)
	v_readfirstlane_b32 s37, v1
	v_readfirstlane_b32 s36, v0
	s_cbranch_scc0 .LBB0_583
	v_mov_b64_e32 v[0:1], s[6:7]
	global_load_dwordx4 v[0:3], v[0:1], off offset:128
	s_lshl_b32 s12, s8, 12
	s_add_i32 s20, s12, 0
	s_add_u32 s40, s36, 0x3900000
	s_addc_u32 s41, s37, 0
	s_add_u32 s21, s36, 0x40000
	s_addc_u32 s59, s37, 0
	v_and_b32_e32 v4, 16, v144
	s_add_u32 s42, s36, 0xaa00000
	v_cmp_gt_u32_e64 s[8:9], 16, v143
	v_cmp_eq_u32_e32 vcc, 0, v4
	s_addc_u32 s43, s37, 0
	s_ashr_i32 s19, s18, 31
	s_and_b64 s[44:45], vcc, s[8:9]
	s_lshl_b64 s[12:13], s[18:19], 12
	v_mov_b32_e32 v149, 0
	s_add_u32 s12, s36, s12
	v_mov_b32_e32 v151, v149
	s_addc_u32 s13, s37, s13
	s_mov_b64 s[10:11], 0x5a00000
	s_mov_b32 s14, 0x5a00000
	v_lshl_add_u64 v[4:5], s[12:13], 0, v[150:151]
	v_lshl_add_u64 v[6:7], v[4:5], 0, s[10:11]
	v_add_co_u32_e32 v4, vcc, s14, v4
	global_load_dwordx4 v[8:11], v[6:7], off offset:1024
	global_load_dwordx4 v[12:15], v[6:7], off offset:2048
	v_addc_co_u32_e32 v5, vcc, 0, v5, vcc
	v_cmp_eq_u32_e64 s[6:7], 0, v143
	v_and_b32_e32 v78, 1, v160
	s_movk_i32 s16, 0x60
	v_cndmask_b32_e64 v24, -16, 16, s[6:7]
	v_mov_b32_e32 v129, v149
	s_lshl_b64 s[50:51], s[18:19], 6
	v_mov_b32_e32 v143, v149
	s_add_i32 s56, s18, s34
	s_mul_hi_i32 s35, s18, 0x300
	s_lshl_b64 s[54:55], s[18:19], 10
	s_ashr_i32 s57, s56, 31
	v_add_u32_e32 v76, s20, v150
	s_mul_i32 s38, s18, 0x300
	v_mov_b32_e32 v51, s35
	s_ashr_i32 s35, s34, 31
	s_lshl_b64 s[48:49], s[18:19], 9
	s_lshl_b64 s[56:57], s[56:57], 12
	s_mov_b32 s39, 0
	v_add_u32_e32 v77, v76, v24
	v_cmp_gt_u32_e64 s[10:11], 16, v141
	v_cmp_gt_u32_e64 s[12:13], 24, v141
	v_cmp_gt_u32_e64 s[14:15], 32, v141
	v_or_b32_e32 v50, s38, v142
	s_mul_hi_i32 s47, s34, 0x300
	s_mul_i32 s46, s34, 0x300
	v_or_b32_e32 v52, s48, v142
	v_mov_b32_e32 v53, s49
	s_lshl_b64 s[48:49], s[34:35], 9
	v_or_b32_e32 v60, s56, v150
	v_mov_b32_e32 v61, s57
	s_lshl_b64 s[56:57], s[34:35], 12
	s_mov_b32 s58, 0x3e38aa3b
	s_movk_i32 s64, 0x7fff
	s_mov_b32 s65, 0xbfb8aa3b
	s_mov_b32 s66, 0x42ce8ed0
	s_mov_b32 s67, 0xc2b17218
	v_mbcnt_hi_u32_b32 v84, -1, v145
	v_mov_b32_e32 v85, 0x3727c5ac
	s_mov_b32 s68, 0xf800000
	v_mov_b32_e32 v86, 0x260
	s_mov_b32 s69, 0xc200000
	s_mov_b32 s70, 0xce00000
	v_mov_b32_e32 v88, 0x7f800000
	s_waitcnt vmcnt(0) lgkmcnt(0)
	v_lshl_add_u64 v[0:1], v[0:1], 0, v[148:149]
	v_lshl_add_u64 v[2:3], v[2:3], 0, v[148:149]
	global_load_dwordx2 v[40:41], v[0:1], off
	global_load_dwordx2 v[42:43], v[0:1], off offset:512
	global_load_dwordx2 v[44:45], v[0:1], off offset:1024
	global_load_dwordx2 v[46:47], v[2:3], off
	global_load_dwordx2 v[48:49], v[2:3], off offset:512
	global_load_dwordx4 v[16:19], v[4:5], off
	global_load_dwordx4 v[20:23], v[6:7], off offset:3072
	v_xor_b32_e32 v0, 16, v141
	v_lshl_add_u32 v79, v0, 1, s20
	v_lshrrev_b32_e32 v0, 4, v141
	v_lshl_or_b32 v3, v78, 7, v146
	v_add_u32_e32 v2, s20, v24
	v_lshl_or_b32 v4, v0, 8, v3
	v_add_u32_e32 v80, s20, v4
	v_add_u32_e32 v81, v2, v4
	v_or_b32_e32 v4, 64, v141
	v_cmp_gt_u32_e64 s[16:17], s16, v4
	v_lshrrev_b32_e32 v4, 4, v4
	v_lshl_or_b32 v3, v4, 8, v3
	v_add_u32_e32 v82, s20, v3
	v_add_u32_e32 v83, v2, v3
	v_lshlrev_b32_e32 v2, 21, v4
	v_lshl_add_u64 v[4:5], s[50:51], 0, v[128:129]
	s_mov_b64 s[50:51], 0x3800000
	v_mov_b32_e32 v3, 0x60
	v_lshl_add_u64 v[54:55], v[4:5], 0, s[50:51]
	v_mad_i64_i32 v[4:5], s[52:53], s18, v3, v[142:143]
	s_mov_b64 s[52:53], 0x3600000
	v_mul_i32_i24_e32 v1, -14, v141
	v_lshlrev_b32_e32 v0, 21, v0
	v_lshl_add_u64 v[56:57], v[4:5], 0, s[52:53]
	v_or_b32_e32 v4, s54, v150
	v_mov_b32_e32 v5, s55
	s_mov_b64 s[54:55], 0x9a00000
	s_lshl_b64 s[50:51], s[34:35], 6
	s_mul_hi_i32 s53, s34, 0x60
	s_mul_i32 s52, s34, 0x60
	v_lshl_add_u64 v[58:59], v[4:5], 0, s[54:55]
	s_lshl_b64 s[54:55], s[34:35], 10
	s_mov_b32 s35, 0xffff0000
	v_lshlrev_b32_e32 v62, 1, v0
	v_lshlrev_b32_e32 v64, 1, v2
	v_add_u32_e32 v87, v76, v1
	s_and_b32 s86, s18, 0x1fff
	s_lshl_b32 s87, s86, 6
	s_add_u32 s88, s21, s87
	s_addc_u32 s89, s59, 0
	v_mov_b64_e32 v[114:115], s[88:89]
	global_load_dwordx4 v[96:99], v[114:115], off
	global_load_dwordx4 v[100:103], v[114:115], off offset:16
	global_load_dwordx4 v[104:107], v[114:115], off offset:32
	global_load_dwordx4 v[108:111], v[114:115], off offset:48
	v_lshlrev_b32_e32 v114, 2, v168
	v_lshl_or_b32 v116, s86, 7, v114
	v_mov_b32_e32 v117, v149
	v_lshl_add_u64 v[114:115], s[40:41], 0, v[116:117]
	global_load_dword v112, v[114:115], off
	global_load_dword v113, v[114:115], off offset:64
	s_branch .LBB0_569

; #define LDS_WAIT() asm volatile("s_waitcnt lgkmcnt(0)" ::: "memory")
; __global__ void __launch_bounds__(NTHREADS, 2) mega_fwd(Args a_unused) {
;     ...
;         for (int m = gw; m < M; m += NGW) {
;             const int b = m >> 13, t = m & 8191;
;             f32x4 c8[4];
; #pragma unroll
;             for (int j = 0; j < 4; ++j) c8[j] = *(const f32x4*)(CS8 + t * 16 + 4 * j);
;             const float c16 = CS16[t * 32 + (lane & 15)], s16 = CS16[t * 32 + 16 + (lane & 15)];
; #pragma unroll
;             for (int j = 0; j < 4; ++j) rb[lane + 64 * j] = hv[j];
;             if (m + NGW < M) {
; #pragma unroll
;                 for (int j = 0; j < 4; ++j) hv[j] = ((const v4u*)(H + (size_t)(m + NGW) * DINP))[lane + 64 * j];
;             }
;             LDS_WAIT();
;             {
;                 const int base = 8 * lane, d0 = 8 * (lane & 7); float v[8];
; #pragma unroll
;                 for (int e = 0; e < 8; ++e) v[e] = bf2f(hb[base + e]);
;                 if (d0 < 16) {
; #pragma unroll
;                     for (int e = 0; e < 8; ++e) { const float c_ = c8[e >> 2][e & 3], s_ = c8[2 + (e >> 2)][e & 3]; const float pr = bf2f(hb[base + e + (d0 == 0 ? 8 : -8)]); v[e] = (d0 == 0) ? v[e] * c_ - pr * s_ : v[e] * c_ + pr * s_; }
.LBB0_569:
	s_and_b32 s19, s18, 0x1fff
	s_lshl_b32 s38, s19, 6
	s_add_u32 s60, s21, s38
	s_addc_u32 s61, s59, 0
	v_mov_b64_e32 v[0:1], s[60:61]
	v_lshlrev_b32_e32 v0, 2, v168
	v_lshl_or_b32 v148, s19, 7, v0
	v_lshl_add_u64 v[0:1], s[40:41], 0, v[148:149]
	s_add_i32 s71, s18, s34
	s_cmpk_gt_i32 s71, 0x3fff
	s_cselect_b64 s[60:61], -1, 0
	s_and_b64 vcc, exec, s[60:61]
	s_waitcnt vmcnt(0) lgkmcnt(0)
	v_mov_b64_e32 v[36:37], v[96:97]
	v_mov_b64_e32 v[38:39], v[98:99]
	v_mov_b64_e32 v[28:29], v[100:101]
	v_mov_b64_e32 v[30:31], v[102:103]
	v_mov_b64_e32 v[32:33], v[104:105]
	v_mov_b64_e32 v[34:35], v[106:107]
	v_mov_b64_e32 v[24:25], v[108:109]
	v_mov_b64_e32 v[26:27], v[110:111]
	v_mov_b32_e32 v89, v112
	v_mov_b32_e32 v90, v113
	s_cmp_lg_u64 s[60:61], 0
	s_cbranch_scc1 .Lp6_nopf
	s_and_b32 s86, s71, 0x1fff
	s_lshl_b32 s87, s86, 6
	s_add_u32 s88, s21, s87
	s_addc_u32 s89, s59, 0
	v_mov_b64_e32 v[114:115], s[88:89]
	global_load_dwordx4 v[96:99], v[114:115], off
	global_load_dwordx4 v[100:103], v[114:115], off offset:16
	global_load_dwordx4 v[104:107], v[114:115], off offset:32
	global_load_dwordx4 v[108:111], v[114:115], off offset:48
	v_lshlrev_b32_e32 v114, 2, v168
	v_lshl_or_b32 v116, s86, 7, v114
	v_mov_b32_e32 v117, v149
	v_lshl_add_u64 v[114:115], s[40:41], 0, v[116:117]
	global_load_dword v112, v[114:115], off
	global_load_dword v113, v[114:115], off offset:64
.Lp6_nopf:
	ds_write_b128 v76, v[16:19]
	ds_write_b128 v76, v[8:11] offset:1024
	ds_write_b128 v76, v[12:15] offset:2048
	ds_write_b128 v76, v[20:23] offset:3072
	s_cbranch_vccnz .LBB0_571
	v_lshl_add_u64 v[0:1], s[36:37], 0, v[60:61]
	v_add_co_u32_e32 v0, vcc, 0x5a00000, v0
	s_nop 1
	v_addc_co_u32_e32 v1, vcc, 0, v1, vcc
	global_load_dwordx4 v[16:19], v[0:1], off
	global_load_dwordx4 v[8:11], v[0:1], off offset:1024
	global_load_dwordx4 v[12:15], v[0:1], off offset:2048
	global_load_dwordx4 v[20:23], v[0:1], off offset:3072
.LBB0_571:
	s_waitcnt lgkmcnt(0)
	ds_read_b128 v[2:5], v76
	s_waitcnt lgkmcnt(0)
	v_lshlrev_b32_e32 v0, 16, v2
	v_lshlrev_b32_e32 v1, 16, v3
	v_and_b32_e32 v70, 0xffff0000, v2
	v_lshlrev_b32_e32 v68, 16, v4
	v_and_b32_e32 v71, 0xffff0000, v3
	v_lshlrev_b32_e32 v69, 16, v5
	v_and_b32_e32 v66, 0xffff0000, v4
	v_and_b32_e32 v67, 0xffff0000, v5
	s_and_saveexec_b64 s[62:63], s[8:9]
	s_cbranch_execz .LBB0_573
	ds_read_b128 v[4:7], v77
	v_mov_b32_e32 v73, v1
	v_mov_b32_e32 v72, v70
	v_mov_b32_e32 v74, v71
	v_mov_b32_e32 v92, v33
	s_waitcnt lgkmcnt(0)
	v_lshlrev_b32_e32 v1, 16, v4
	v_mul_f32_e32 v1, v32, v1
	v_cndmask_b32_e64 v2, v1, -v1, s[6:7]
	v_and_b32_e32 v70, 0xffff0000, v4
	v_lshlrev_b32_e32 v71, 16, v5
	v_mov_b32_e32 v93, v34
	v_fmac_f32_e32 v2, v36, v0
	v_mov_b32_e32 v0, v37
	v_mov_b32_e32 v1, v38
	v_pk_mul_f32 v[70:71], v[92:93], v[70:71]
	v_and_b32_e32 v4, 0xffff0000, v5
	v_pk_fma_f32 v[92:93], v[0:1], v[72:73], v[70:71] neg_lo:[0,0,1] neg_hi:[0,0,1]
	v_pk_fma_f32 v[0:1], v[0:1], v[72:73], v[70:71]
	v_lshlrev_b32_e32 v5, 16, v6
	v_pk_mov_b32 v[72:73], v[34:35], v[24:25] op_sel:[1,0]
	v_mov_b32_e32 v75, v68
	v_cndmask_b32_e64 v70, v0, v92, s[6:7]
	v_cndmask_b32_e64 v63, v1, v93, s[6:7]
	v_pk_mov_b32 v[0:1], v[38:39], v[28:29] op_sel:[1,0]
	v_pk_mul_f32 v[4:5], v[72:73], v[4:5]
	v_mov_b32_e32 v68, v66
	v_pk_fma_f32 v[72:73], v[0:1], v[74:75], v[4:5] neg_lo:[0,0,1] neg_hi:[0,0,1]
	v_pk_fma_f32 v[0:1], v[0:1], v[74:75], v[4:5]
	v_lshlrev_b32_e32 v5, 16, v7
	v_cndmask_b32_e64 v71, v0, v72, s[6:7]
	v_cndmask_b32_e64 v65, v1, v73, s[6:7]
	v_and_b32_e32 v4, 0xffff0000, v6
	v_mov_b32_e32 v72, v25
	v_mov_b32_e32 v73, v26
	v_mov_b32_e32 v0, v29
	v_mov_b32_e32 v1, v30
	v_pk_mul_f32 v[4:5], v[72:73], v[4:5]
	s_nop 0
	v_pk_fma_f32 v[72:73], v[0:1], v[68:69], v[4:5] neg_lo:[0,0,1] neg_hi:[0,0,1]
	v_pk_fma_f32 v[0:1], v[0:1], v[68:69], v[4:5]
	v_mov_b32_e32 v4, v31
	v_cndmask_b32_e64 v66, v0, v72, s[6:7]
	v_cndmask_b32_e64 v69, v1, v73, s[6:7]
	v_and_b32_e32 v1, 0xffff0000, v7
	v_mov_b32_e32 v5, v27
	v_mov_b32_e32 v0, v67
	v_pk_mul_f32 v[0:1], v[4:5], v[0:1]
	v_mov_b32_e32 v68, v65
	v_sub_f32_e32 v3, v0, v1
	v_add_f32_e32 v0, v0, v1
	v_cndmask_b32_e64 v67, v0, v3, s[6:7]
	v_mov_b64_e32 v[0:1], v[2:3]
	v_mov_b32_e32 v1, v63
; __device__ __forceinline__ unsigned pk2(float lo, float hi) { return f2bf(lo) | (f2bf(hi) << 16); }
; __global__ void __launch_bounds__(NTHREADS, 2) mega_fwd(Args a_unused) {
;     ...
;                 if (d0 < 16) {
; #pragma unroll
;                     for (int e = 0; e < 8; ++e) { const float c_ = c8[e >> 2][e & 3], s_ = c8[2 + (e >> 2)][e & 3]; const float pr = bf2f(hb[base + e + (d0 == 0 ? 8 : -8)]); v[e] = (d0 == 0) ? v[e] * c_ - pr * s_ : v[e] * c_ + pr * s_; }
;                 }
;                 v4u o; o.x = pk2(v[0] * QS_NSA, v[1] * QS_NSA); o.y = pk2(v[2] * QS_NSA, v[3] * QS_NSA); o.z = pk2(v[4] * QS_NSA, v[5] * QS_NSA); o.w = pk2(v[6] * QS_NSA, v[7] * QS_NSA);
;                 *(v4u*)(QN + (size_t)m * 512 + base) = o;
;             }
; #pragma unroll
;             for (int it = 0; it < 2; ++it) {
;                 const int ch = lane + 64 * it;
;                 if (ch < 96) {
;                     const int seg = ch >> 4, w = ch & 15, g = w >> 3, d0 = 8 * (w & 7), base = 512 + 128 * seg + 64 * g + d0; float v[8];
; #pragma unroll
;                     for (int e = 0; e < 8; ++e) v[e] = bf2f(hb[base + e]);
;                     if ((seg & 1) == 0 && d0 < 16) {
; #pragma unroll
;                         for (int e = 0; e < 8; ++e) { const float c_ = c8[e >> 2][e & 3], s_ = c8[2 + (e >> 2)][e & 3]; const float pr = bf2f(hb[base + e + (d0 == 0 ? 8 : -8)]); v[e] = (d0 == 0) ? v[e] * c_ - pr * s_ : v[e] * c_ + pr * s_; }
;                     }
;                     v4u o; o.x = pk2(v[0], v[1]); o.y = pk2(v[2], v[3]); o.z = pk2(v[4], v[5]); o.w = pk2(v[6], v[7]);
;                     *(v4u*)(KV6 + (size_t)seg * KV6_SEG + ((size_t)(b * 2 + g) * T + t) * 64 + d0) = o;
.LBB0_573:
	s_or_b64 exec, exec, s[62:63]
	v_pk_mul_f32 v[2:3], v[70:71], s[58:59] op_sel_hi:[1,0]
	v_pk_mul_f32 v[6:7], v[66:67], s[58:59] op_sel_hi:[1,0]
	v_pk_mul_f32 v[0:1], v[0:1], s[58:59] op_sel_hi:[1,0]
	v_pk_mul_f32 v[4:5], v[68:69], s[58:59] op_sel_hi:[1,0]
	v_bfe_u32 v63, v7, 16, 1
	v_bfe_u32 v65, v6, 16, 1
	v_bfe_u32 v66, v3, 16, 1
	v_bfe_u32 v67, v2, 16, 1
	v_add3_u32 v67, v2, v67, s64
	v_add3_u32 v66, v3, v66, s64
	v_add3_u32 v2, v6, v65, s64
	v_add3_u32 v3, v7, v63, s64
	v_bfe_u32 v6, v0, 16, 1
	v_bfe_u32 v7, v1, 16, 1
	v_bfe_u32 v63, v4, 16, 1
	v_bfe_u32 v65, v5, 16, 1
	v_add3_u32 v5, v5, v65, s64
	v_add3_u32 v4, v4, v63, s64
	v_add3_u32 v1, v1, v7, s64
	v_add3_u32 v0, v0, v6, s64
	v_lshrrev_b32_e32 v0, 16, v0
	v_lshrrev_b32_e32 v1, 16, v1
	v_lshrrev_b32_e32 v4, 16, v4
	v_lshrrev_b32_e32 v5, 16, v5
	v_and_or_b32 v3, v3, s35, v5
	v_and_or_b32 v2, v2, s35, v4
	v_and_or_b32 v1, v66, s35, v1
	v_and_or_b32 v0, v67, s35, v0
	v_lshl_add_u64 v[4:5], s[36:37], 0, v[58:59]
	global_store_dwordx4 v[4:5], v[0:3], off sc0 sc1
	ds_read_b128 v[2:5], v80 offset:1024
	s_waitcnt lgkmcnt(0)
	v_lshlrev_b32_e32 v75, 16, v3
	v_lshlrev_b32_e32 v0, 16, v2
	v_and_b32_e32 v74, 0xffff0000, v2
	v_lshlrev_b32_e32 v73, 16, v4
	v_and_b32_e32 v72, 0xffff0000, v3
	v_lshlrev_b32_e32 v69, 16, v5
	v_and_b32_e32 v68, 0xffff0000, v4
	v_and_b32_e32 v70, 0xffff0000, v5
	s_and_saveexec_b64 s[62:63], s[44:45]
	s_cbranch_execz .LBB0_575
	ds_read_b128 v[2:5], v81 offset:1024
	v_mov_b32_e32 v6, v37
	v_mov_b32_e32 v7, v38
	s_waitcnt lgkmcnt(0)
	v_lshlrev_b32_e32 v1, 16, v2
	v_mul_f32_e32 v1, v32, v1
	v_and_b32_e32 v66, 0xffff0000, v2
	v_cndmask_b32_e64 v2, v1, -v1, s[6:7]
	v_lshlrev_b32_e32 v67, 16, v3
	v_fmac_f32_e32 v2, v36, v0
	v_mov_b32_e32 v0, v33
	v_mov_b32_e32 v1, v34
	v_pk_mul_f32 v[0:1], v[0:1], v[66:67]
	v_and_b32_e32 v71, 0xffff0000, v5
	v_pk_fma_f32 v[66:67], v[6:7], v[74:75], v[0:1] neg_lo:[0,0,1] neg_hi:[0,0,1]
	v_pk_fma_f32 v[0:1], v[6:7], v[74:75], v[0:1]
	v_and_b32_e32 v6, 0xffff0000, v3
	v_cndmask_b32_e64 v74, v0, v66, s[6:7]
	v_cndmask_b32_e64 v75, v1, v67, s[6:7]
	v_lshlrev_b32_e32 v7, 16, v4
	v_pk_mov_b32 v[66:67], v[34:35], v[24:25] op_sel:[1,0]
	v_pk_mov_b32 v[0:1], v[38:39], v[28:29] op_sel:[1,0]
	v_pk_mul_f32 v[6:7], v[66:67], v[6:7]
	s_nop 0
	v_pk_fma_f32 v[66:67], v[0:1], v[72:73], v[6:7] neg_lo:[0,0,1] neg_hi:[0,0,1]
	v_pk_fma_f32 v[0:1], v[0:1], v[72:73], v[6:7]
	v_lshlrev_b32_e32 v7, 16, v5
	v_cndmask_b32_e64 v72, v0, v66, s[6:7]
	v_cndmask_b32_e64 v73, v1, v67, s[6:7]
	v_and_b32_e32 v6, 0xffff0000, v4
	v_mov_b32_e32 v66, v25
	v_mov_b32_e32 v67, v26
	v_mov_b32_e32 v0, v29
	v_mov_b32_e32 v1, v30
	v_pk_mul_f32 v[6:7], v[66:67], v[6:7]
	s_nop 0
	v_pk_fma_f32 v[66:67], v[0:1], v[68:69], v[6:7] neg_lo:[0,0,1] neg_hi:[0,0,1]
	v_pk_fma_f32 v[0:1], v[0:1], v[68:69], v[6:7]
	s_nop 0
	v_cndmask_b32_e64 v68, v0, v66, s[6:7]
	v_cndmask_b32_e64 v69, v1, v67, s[6:7]
	v_mov_b32_e32 v0, v31
	v_mov_b32_e32 v1, v27
	v_pk_mul_f32 v[0:1], v[0:1], v[70:71]
	s_nop 0
	v_sub_f32_e32 v3, v0, v1
	v_add_f32_e32 v0, v0, v1
	v_cndmask_b32_e64 v70, v0, v3, s[6:7]
	v_mov_b64_e32 v[0:1], v[2:3]
.LBB0_575:
	s_or_b64 exec, exec, s[62:63]
	s_ashr_i32 s18, s18, 12
	v_and_or_b32 v2, s18, -2, v78
	v_ashrrev_i32_e32 v3, 31, v2
	v_bfe_u32 v1, v0, 16, 1
	v_lshlrev_b64 v[2:3], 20, v[2:3]
	v_add3_u32 v0, v0, v1, s64
	v_bfe_u32 v1, v74, 16, 1
	v_lshl_add_u64 v[2:3], s[42:43], 0, v[2:3]
	s_lshl_b32 s38, s19, 7
	v_lshrrev_b32_e32 v0, 16, v0
	v_add3_u32 v1, v74, v1, s64
	v_lshl_add_u64 v[2:3], v[2:3], 0, s[38:39]
	v_mov_b32_e32 v147, v149
	v_and_or_b32 v0, v1, s35, v0
	v_bfe_u32 v1, v75, 16, 1
	v_lshl_add_u64 v[66:67], v[2:3], 0, v[146:147]
	v_add3_u32 v1, v75, v1, s64
	v_bfe_u32 v2, v72, 16, 1
	v_lshrrev_b32_e32 v1, 16, v1
	v_add3_u32 v2, v72, v2, s64
	v_and_or_b32 v1, v2, s35, v1
	v_bfe_u32 v2, v73, 16, 1
	v_add3_u32 v2, v73, v2, s64
	v_bfe_u32 v3, v68, 16, 1
	v_lshrrev_b32_e32 v2, 16, v2
	v_add3_u32 v3, v68, v3, s64
	v_and_or_b32 v2, v3, s35, v2
	v_bfe_u32 v3, v69, 16, 1
	v_add3_u32 v3, v69, v3, s64
	v_bfe_u32 v4, v70, 16, 1
	v_lshrrev_b32_e32 v3, 16, v3
	v_add3_u32 v4, v70, v4, s64
	v_mov_b32_e32 v63, v149
	v_and_or_b32 v3, v4, s35, v3
	v_lshl_add_u64 v[4:5], v[66:67], 0, v[62:63]
	global_store_dwordx4 v[4:5], v[0:3], off sc0 sc1
	s_and_saveexec_b64 s[18:19], s[16:17]
	s_cbranch_execz .LBB0_579
	ds_read_b128 v[2:5], v82 offset:1024
	s_waitcnt lgkmcnt(0)
	v_lshlrev_b32_e32 v0, 16, v2
	v_lshlrev_b32_e32 v75, 16, v3
	v_and_b32_e32 v74, 0xffff0000, v2
	v_lshlrev_b32_e32 v73, 16, v4
	v_and_b32_e32 v72, 0xffff0000, v3
	v_lshlrev_b32_e32 v69, 16, v5
	v_and_b32_e32 v68, 0xffff0000, v4
	v_and_b32_e32 v70, 0xffff0000, v5
	s_and_saveexec_b64 s[62:63], s[44:45]
	s_cbranch_execz .LBB0_578
	ds_read_b128 v[2:5], v83 offset:1024
	v_mov_b32_e32 v6, v37
	v_mov_b32_e32 v7, v38
	s_waitcnt lgkmcnt(0)
	v_lshlrev_b32_e32 v1, 16, v2
	v_mul_f32_e32 v1, v32, v1
	v_and_b32_e32 v92, 0xffff0000, v2
	v_cndmask_b32_e64 v2, v1, -v1, s[6:7]
	v_lshlrev_b32_e32 v93, 16, v3
	v_fmac_f32_e32 v2, v36, v0
	v_mov_b32_e32 v0, v33
	v_mov_b32_e32 v1, v34
	v_pk_mul_f32 v[0:1], v[0:1], v[92:93]
	v_and_b32_e32 v71, 0xffff0000, v5
	v_pk_fma_f32 v[32:33], v[6:7], v[74:75], v[0:1] neg_lo:[0,0,1] neg_hi:[0,0,1]
	v_pk_fma_f32 v[0:1], v[6:7], v[74:75], v[0:1]
	v_and_b32_e32 v6, 0xffff0000, v3
	v_cndmask_b32_e64 v74, v0, v32, s[6:7]
	v_cndmask_b32_e64 v75, v1, v33, s[6:7]
	v_lshlrev_b32_e32 v7, 16, v4
	v_pk_mov_b32 v[32:33], v[34:35], v[24:25] op_sel:[1,0]
	v_pk_mov_b32 v[0:1], v[38:39], v[28:29] op_sel:[1,0]
	v_pk_mul_f32 v[6:7], v[32:33], v[6:7]
	v_mov_b32_e32 v24, v25
	v_pk_fma_f32 v[32:33], v[0:1], v[72:73], v[6:7] neg_lo:[0,0,1] neg_hi:[0,0,1]
	v_pk_fma_f32 v[0:1], v[0:1], v[72:73], v[6:7]
	v_lshlrev_b32_e32 v7, 16, v5
	v_and_b32_e32 v6, 0xffff0000, v4
	v_mov_b32_e32 v25, v26
	v_cndmask_b32_e64 v72, v0, v32, s[6:7]
	v_cndmask_b32_e64 v73, v1, v33, s[6:7]
	v_mov_b32_e32 v0, v29
	v_mov_b32_e32 v1, v30
	v_pk_mul_f32 v[6:7], v[24:25], v[6:7]
	v_mov_b32_e32 v26, v31
	v_pk_fma_f32 v[24:25], v[0:1], v[68:69], v[6:7] neg_lo:[0,0,1] neg_hi:[0,0,1]
	v_pk_fma_f32 v[0:1], v[0:1], v[68:69], v[6:7]
	s_nop 0
	v_cndmask_b32_e64 v68, v0, v24, s[6:7]
	v_cndmask_b32_e64 v69, v1, v25, s[6:7]
	v_pk_mul_f32 v[0:1], v[26:27], v[70:71]
	s_nop 0
	v_sub_f32_e32 v3, v0, v1
	v_add_f32_e32 v0, v0, v1
	v_cndmask_b32_e64 v70, v0, v3, s[6:7]
	v_mov_b64_e32 v[0:1], v[2:3]

; __device__ __forceinline__ unsigned cvtpk(float lo, float hi) { f32x2_t v = {lo, hi}; bf16x2_t b = __builtin_convertvector(v, bf16x2_t); return __builtin_bit_cast(unsigned, b); }
; #define ATT_BAR() asm volatile("s_waitcnt lgkmcnt(0)\n\ts_barrier" ::: "memory")
; __device__ __forceinline__ f32x4 unpk_lo(const v4u& w) { return (f32x4){__uint_as_float(w.x << 16), __uint_as_float(w.x & 0xffff0000u), __uint_as_float(w.y << 16), __uint_as_float(w.y & 0xffff0000u)}; }
; __device__ __forceinline__ f32x4 unpk_hi(const v4u& w) { return (f32x4){__uint_as_float(w.z << 16), __uint_as_float(w.z & 0xffff0000u), __uint_as_float(w.w << 16), __uint_as_float(w.w & 0xffff0000u)}; }
; template <int DQK, int MODE> __device__ __forceinline__ void attn_pass(LAS unsigned char* lds, const bf16* K0, int p0, const bf16* K1, int p1, const bf16* V, int pv, int tlo, int thi, ...
;     ...
;     if (grp == 0) ATT_BAR(); else __builtin_amdgcn_s_setprio(0);
; #pragma unroll
;     for (int i = 0; i < 2; ++i) {
;         const float lt = rows_sum(l[i]);
;         const float iv = lt > 0.f ? 1.0f / lt : 0.f;
;         mfin[i] = m[i]; linv[i] = iv;
; #pragma unroll
;         for (int dt = 0; dt < 4; ++dt) o[i][dt] = o[i][dt] * iv;
;     }
; __device__ __forceinline__ void nsa_item(LAS unsigned char* lds, const NsaPtrs& P, int b, int g, int qb, int tid) {
;     ...
; #pragma unroll
;     for (int i = 0; i < 2; ++i) {
;         const float gw = P.GATES[((size_t)b * T + tpos[i]) * 24 + g * 12 + hh * 3 + 2];
;         bf16* orow = P.OCAT + ((size_t)b * T + tpos[i]) * 1024 + (g * 4 + hh) * 64 + 4 * fq;
; #pragma unroll
;         for (int dt = 0; dt < 4; ++dt) { const v4u w = ocl[(i * 2 + (dt >> 1)) * NTHREADS + tid]; const f32x4 r = ((dt & 1) ? unpk_hi(w) : unpk_lo(w)) + o[i][dt] * gw;
;             *(unsigned long long*)(orow + 16 * dt) = (unsigned long long)cvtpk(r[0], r[1]) | ((unsigned long long)cvtpk(r[2], r[3]) << 32); }
;     }
.LBB0_982:
	s_add_u32 s6, s56, s18
	s_addc_u32 s7, s57, 0
	v_mov_b32_e32 v153, v147
	v_lshl_add_u64 v[36:37], s[6:7], 0, v[152:153]
	v_lshl_add_u64 v[32:33], v[36:37], 0, v[124:125]
	v_mov_b32_e32 v38, v200
	v_lshl_add_u64 v[36:37], v[36:37], 0, v[122:123]
	v_mov_b32_e32 v36, v211
	v_mov_b32_e32 v39, v105
	v_mov_b32_e32 v44, v104
	v_mov_b32_e32 v113, v147
	v_permlane16_swap_b32_e32 v105, v39
	v_permlane16_swap_b32_e32 v104, v44
	v_mov_b32_e32 v155, v147
	v_lshl_add_u64 v[42:43], s[54:55], 0, v[112:113]
	v_add_f32_e32 v45, v105, v39
	v_add_f32_e32 v44, v104, v44
	ds_read_b128 v[32:35], v173
	v_lshl_add_u64 v[42:43], v[42:43], 0, v[154:155]
	v_mov_b32_e32 v47, v45
	v_mov_b32_e32 v46, v44
	v_lshlrev_b64 v[40:41], 11, v[120:121]
	s_waitcnt lgkmcnt(0)
	v_lshlrev_b64 v[34:35], 11, v[118:119]
	v_lshl_add_u64 v[42:43], v[42:43], 0, s[42:43]
	v_permlane32_swap_b32_e32 v45, v47
	v_permlane32_swap_b32_e32 v44, v46
	v_lshl_add_u64 v[40:41], v[42:43], 0, v[40:41]
	v_lshl_add_u64 v[34:35], v[42:43], 0, v[34:35]
	v_pk_add_f32 v[42:43], v[44:45], v[46:47]
	v_lshlrev_b32_e32 v44, 16, v32
	v_div_scale_f32 v37, s[6:7], v43, v43, 1.0
	v_rcp_f32_e32 v46, v37
	v_div_scale_f32 v47, s[6:7], v42, v42, 1.0
	s_waitcnt vmcnt(0)
	v_rcp_f32_e32 v48, v47
	v_fma_f32 v50, -v37, v46, 1.0
	v_div_scale_f32 v39, vcc, 1.0, v43, 1.0
	v_fmac_f32_e32 v46, v50, v46
	v_fma_f32 v51, -v47, v48, 1.0
	v_mul_f32_e32 v50, v39, v46
	v_fmac_f32_e32 v48, v51, v48
	v_fma_f32 v51, -v37, v50, v39
	v_fmac_f32_e32 v50, v51, v46
	v_fma_f32 v37, -v37, v50, v39
	v_div_fmas_f32 v37, v37, v46, v50
	v_div_fixup_f32 v37, v37, v43, 1.0
	v_cmp_lt_f32_e32 vcc, 0, v43
	v_and_b32_e32 v45, 0xffff0000, v32
	v_lshlrev_b32_e32 v32, 16, v33
	v_cndmask_b32_e32 v46, 0, v37, vcc
	v_and_b32_e32 v33, 0xffff0000, v33
	v_pk_mul_f32 v[28:29], v[28:29], v[46:47] op_sel_hi:[1,0]
	v_pk_mul_f32 v[30:31], v[30:31], v[46:47] op_sel_hi:[1,0]
	v_pk_mul_f32 v[24:25], v[24:25], v[46:47] op_sel_hi:[1,0]
	v_pk_mul_f32 v[26:27], v[26:27], v[46:47] op_sel_hi:[1,0]
	v_pk_mul_f32 v[20:21], v[20:21], v[46:47] op_sel_hi:[1,0]
	v_pk_mul_f32 v[22:23], v[22:23], v[46:47] op_sel_hi:[1,0]
	v_div_scale_f32 v49, s[6:7], 1.0, v42, 1.0
	s_mov_b64 vcc, s[6:7]
	v_pk_mul_f32 v[16:17], v[16:17], v[46:47] op_sel_hi:[1,0]
	v_pk_mul_f32 v[18:19], v[18:19], v[46:47] op_sel_hi:[1,0]
	s_mov_b64 s[6:7], 0
	v_pk_fma_f32 v[30:31], v[38:39], v[30:31], v[32:33] op_sel_hi:[0,1,1]
	v_pk_fma_f32 v[28:29], v[38:39], v[28:29], v[44:45] op_sel_hi:[0,1,1]
	v_cvt_pk_bf16_f32 v28, v28, v29
	v_cvt_pk_bf16_f32 v29, v30, v31
	global_store_dwordx2 v[40:41], v[28:29], off
	ds_read_b128 v[28:31], v173
	v_mul_f32_e32 v32, v49, v48
	v_fma_f32 v33, -v47, v32, v49
	v_fmac_f32_e32 v32, v33, v48
	s_waitcnt lgkmcnt(0)
	v_lshlrev_b32_e32 v28, 16, v30
	v_and_b32_e32 v29, 0xffff0000, v30
	v_lshlrev_b32_e32 v30, 16, v31
	v_and_b32_e32 v31, 0xffff0000, v31
	v_pk_fma_f32 v[26:27], v[38:39], v[26:27], v[30:31] op_sel_hi:[0,1,1]
	v_pk_fma_f32 v[24:25], v[38:39], v[24:25], v[28:29] op_sel_hi:[0,1,1]
	v_cvt_pk_bf16_f32 v24, v24, v25
	v_cvt_pk_bf16_f32 v25, v26, v27
	global_store_dwordx2 v[40:41], v[24:25], off offset:32
	ds_read_b128 v[24:27], v173 offset:8192
	v_fma_f32 v28, -v47, v32, v49
	s_waitcnt lgkmcnt(0)
	v_lshlrev_b32_e32 v26, 16, v24
	v_and_b32_e32 v27, 0xffff0000, v24
	v_lshlrev_b32_e32 v24, 16, v25
	v_and_b32_e32 v25, 0xffff0000, v25
	v_pk_fma_f32 v[22:23], v[38:39], v[22:23], v[24:25] op_sel_hi:[0,1,1]
	v_pk_fma_f32 v[20:21], v[38:39], v[20:21], v[26:27] op_sel_hi:[0,1,1]
	v_cvt_pk_bf16_f32 v20, v20, v21
	v_cvt_pk_bf16_f32 v21, v22, v23
	global_store_dwordx2 v[40:41], v[20:21], off offset:64
	ds_read_b128 v[20:23], v173 offset:8192
	s_waitcnt lgkmcnt(0)
	v_div_fmas_f32 v20, v28, v48, v32
	v_div_fixup_f32 v24, v20, v42, 1.0
	v_cmp_lt_f32_e32 vcc, 0, v42
	v_lshlrev_b32_e32 v20, 16, v22
	v_and_b32_e32 v21, 0xffff0000, v22
	v_lshlrev_b32_e32 v22, 16, v23
	v_and_b32_e32 v23, 0xffff0000, v23
	v_pk_fma_f32 v[18:19], v[38:39], v[18:19], v[22:23] op_sel_hi:[0,1,1]
	v_pk_fma_f32 v[16:17], v[38:39], v[16:17], v[20:21] op_sel_hi:[0,1,1]
	v_cvt_pk_bf16_f32 v16, v16, v17
	v_cvt_pk_bf16_f32 v17, v18, v19
	global_store_dwordx2 v[40:41], v[16:17], off offset:96
	ds_read_b128 v[16:19], v173 offset:16384
	s_waitcnt lgkmcnt(0)
	v_cndmask_b32_e32 v18, 0, v24, vcc
	s_and_b64 vcc, exec, s[52:53]
	v_pk_mul_f32 v[12:13], v[12:13], v[18:19] op_sel_hi:[1,0]
	v_pk_mul_f32 v[14:15], v[14:15], v[18:19] op_sel_hi:[1,0]
	v_lshlrev_b32_e32 v20, 16, v16
	v_and_b32_e32 v21, 0xffff0000, v16
	v_lshlrev_b32_e32 v16, 16, v17
	v_and_b32_e32 v17, 0xffff0000, v17
	v_pk_fma_f32 v[14:15], v[14:15], v[36:37], v[16:17] op_sel_hi:[1,0,1]
	v_pk_fma_f32 v[12:13], v[12:13], v[36:37], v[20:21] op_sel_hi:[1,0,1]
	v_pk_mul_f32 v[8:9], v[8:9], v[18:19] op_sel_hi:[1,0]
	v_cvt_pk_bf16_f32 v12, v12, v13
	v_cvt_pk_bf16_f32 v13, v14, v15
	global_store_dwordx2 v[34:35], v[12:13], off
	ds_read_b128 v[12:15], v173 offset:16384
	v_pk_mul_f32 v[10:11], v[10:11], v[18:19] op_sel_hi:[1,0]
	v_pk_mul_f32 v[4:5], v[4:5], v[18:19] op_sel_hi:[1,0]
	v_pk_mul_f32 v[6:7], v[6:7], v[18:19] op_sel_hi:[1,0]
	v_pk_mul_f32 v[0:1], v[0:1], v[18:19] op_sel_hi:[1,0]
	s_waitcnt lgkmcnt(0)
	v_lshlrev_b32_e32 v12, 16, v14
	v_and_b32_e32 v13, 0xffff0000, v14
	v_lshlrev_b32_e32 v14, 16, v15
	v_and_b32_e32 v15, 0xffff0000, v15
	v_pk_fma_f32 v[10:11], v[10:11], v[36:37], v[14:15] op_sel_hi:[1,0,1]
	v_pk_fma_f32 v[8:9], v[8:9], v[36:37], v[12:13] op_sel_hi:[1,0,1]
	v_pk_mul_f32 v[2:3], v[2:3], v[18:19] op_sel_hi:[1,0]
	v_cvt_pk_bf16_f32 v8, v8, v9
	v_cvt_pk_bf16_f32 v9, v10, v11
	global_store_dwordx2 v[34:35], v[8:9], off offset:32
	ds_read_b128 v[8:11], v173 offset:24576
	s_waitcnt lgkmcnt(0)
	v_lshlrev_b32_e32 v10, 16, v8
	v_and_b32_e32 v11, 0xffff0000, v8
	v_lshlrev_b32_e32 v8, 16, v9
	v_and_b32_e32 v9, 0xffff0000, v9
	v_pk_fma_f32 v[6:7], v[6:7], v[36:37], v[8:9] op_sel_hi:[1,0,1]
	v_pk_fma_f32 v[4:5], v[4:5], v[36:37], v[10:11] op_sel_hi:[1,0,1]
	s_nop 0
	v_cvt_pk_bf16_f32 v4, v4, v5
	v_cvt_pk_bf16_f32 v5, v6, v7
	global_store_dwordx2 v[34:35], v[4:5], off offset:64
	ds_read_b128 v[4:7], v173 offset:24576
	s_waitcnt lgkmcnt(0)
	v_lshlrev_b32_e32 v4, 16, v6
	v_and_b32_e32 v5, 0xffff0000, v6
	v_lshlrev_b32_e32 v6, 16, v7
	v_and_b32_e32 v7, 0xffff0000, v7
	v_pk_fma_f32 v[2:3], v[2:3], v[36:37], v[6:7] op_sel_hi:[1,0,1]
	v_pk_fma_f32 v[0:1], v[0:1], v[36:37], v[4:5] op_sel_hi:[1,0,1]
	s_nop 0
	v_cvt_pk_bf16_f32 v0, v0, v1
	v_cvt_pk_bf16_f32 v1, v2, v3
	global_store_dwordx2 v[34:35], v[0:1], off offset:96
	s_cbranch_vccnz .LBB0_866

; #define LAS __attribute__((address_space(3)))
; __device__ __forceinline__ v4u pack8(const f32x4& a, const f32x4& b) { return (v4u){cvtpk(a[0], a[1]), cvtpk(a[2], a[3]), cvtpk(b[0], b[1]), cvtpk(b[2], b[3])}; }
; template <int DQK, int MODE> __device__ __forceinline__ void attn_pass(LAS unsigned char* lds, const bf16* K0, int p0, const bf16* K1, int p1, const bf16* V, int pv, int tlo, int thi, ...
;     ...
; #pragma unroll
;     for (int i = 0; i < 2; ++i) {
;         const float lt = rows_sum(l[i]);
;         const float iv = lt > 0.f ? 1.0f / lt : 0.f;
;         mfin[i] = m[i]; linv[i] = iv;
; #pragma unroll
;         for (int dt = 0; dt < 4; ++dt) o[i][dt] = o[i][dt] * iv;
;     }
; __device__ __forceinline__ void nsa_item(LAS unsigned char* lds, const NsaPtrs& P, int b, int g, int qb, int tid) {
;     ...
; #pragma unroll
;     for (int i = 0; i < 2; ++i) { const float gc = P.GATES[((size_t)b * T + tpos[i]) * 24 + g * 12 + hh * 3 + 0];
;         ocl[(i * 2 + 0) * NTHREADS + tid] = pack8(o[i][0] * gc, o[i][1] * gc); ocl[(i * 2 + 1) * NTHREADS + tid] = pack8(o[i][2] * gc, o[i][3] * gc); }
;     ...
;     int tid_i = tid; asm volatile("" : "+v"(tid_i)); const int fr_i = tid_i & 15, fq_i = (tid_i & 63) >> 4; asm volatile("" : "+s"(Kc));
;     v4u kpre = *(const v4u*)(Kc + (size_t)(tid_i >> 3) * 64 + 8 * (tid_i & 7));
;     for (int t = 0; t <= thi_c; ++t) {
;         __syncthreads();
;         { const int key = tid_i >> 3, c = tid_i & 7; *(LAS v4u*)(lds + k_off<64>(key, c)) = kpre; }
;         __syncthreads();
;         if (t < thi_c) kpre = *(const v4u*)(Kc + (size_t)(64 * (t + 1) + (tid_i >> 3)) * 64 + 8 * (tid_i & 7));
.LBB0_1018:
	s_add_u32 s56, s54, 0x3600000
	s_addc_u32 s57, s55, 0
	v_mov_b32_e32 v115, v147
	v_lshl_add_u64 v[120:121], s[46:47], 0, v[114:115]
	s_waitcnt vmcnt(0) lgkmcnt(0)
	v_mov_b64_e32 v[48:49], s[56:57]
	v_mad_u64_u32 v[50:51], s[6:7], v120, s84, v[48:49]
	v_mad_i32_i24 v51, v121, s84, v51
	s_lshl_b32 s18, s71, 2
	v_lshl_add_u64 v[50:51], v[50:51], 0, s[18:19]
	v_mov_b32_e32 v153, v147
	v_lshl_add_u64 v[128:129], v[50:51], 0, v[152:153]
	global_load_dword v50, v[128:129], off
	global_load_dword v100, v[128:129], off offset:4
	global_load_dword v200, v[128:129], off offset:8
	v_mov_b32_e32 v51, v104
	v_mov_b32_e32 v52, v105
	s_nop 0
	v_permlane16_swap_b32_e32 v104, v51
	v_permlane16_swap_b32_e32 v105, v52
	v_add_f32_e32 v53, v104, v51
	v_add_f32_e32 v52, v105, v52
	v_mov_b32_e32 v55, v53
	v_mov_b32_e32 v54, v52
	s_nop 0
	v_permlane32_swap_b32_e32 v53, v55
	v_permlane32_swap_b32_e32 v52, v54
	v_pk_add_f32 v[52:53], v[52:53], v[54:55]
	v_mov_b32_e32 v117, v147
	v_div_scale_f32 v51, s[6:7], v53, v53, 1.0
	v_lshl_add_u64 v[118:119], s[46:47], 0, v[116:117]
	v_rcp_f32_e32 v54, v51
	v_mad_u64_u32 v[48:49], s[6:7], v118, s84, v[48:49]
	v_mad_i32_i24 v49, v119, s84, v49
	v_lshl_add_u64 v[48:49], v[48:49], 0, s[18:19]
	v_lshl_add_u64 v[126:127], v[48:49], 0, v[152:153]
	global_load_dword v251, v[126:127], off
	global_load_dword v101, v[126:127], off offset:4
	global_load_dword v211, v[126:127], off offset:8
	v_fma_f32 v48, -v51, v54, 1.0
	v_div_scale_f32 v55, vcc, 1.0, v53, 1.0
	v_fmac_f32_e32 v54, v48, v54
	v_mul_f32_e32 v48, v55, v54
	v_fma_f32 v49, -v51, v48, v55
	v_fmac_f32_e32 v48, v49, v54
	v_fma_f32 v49, -v51, v48, v55
	v_div_fmas_f32 v48, v49, v54, v48
	v_div_fixup_f32 v48, v48, v53, 1.0
	v_cmp_lt_f32_e32 vcc, 0, v53
	v_mad_u64_u32 v[124:125], s[6:7], v120, s84, 0
	s_nop 0
	v_cndmask_b32_e32 v64, 0, v48, vcc
	v_pk_mul_f32 v[44:45], v[44:45], v[64:65] op_sel_hi:[1,0]
	v_pk_mul_f32 v[46:47], v[46:47], v[64:65] op_sel_hi:[1,0]
	v_pk_mul_f32 v[40:41], v[40:41], v[64:65] op_sel_hi:[1,0]
	v_pk_mul_f32 v[42:43], v[42:43], v[64:65] op_sel_hi:[1,0]
	v_pk_mul_f32 v[36:37], v[36:37], v[64:65] op_sel_hi:[1,0]
	v_pk_mul_f32 v[38:39], v[38:39], v[64:65] op_sel_hi:[1,0]
	v_pk_mul_f32 v[32:33], v[32:33], v[64:65] op_sel_hi:[1,0]
	v_pk_mul_f32 v[34:35], v[34:35], v[64:65] op_sel_hi:[1,0]
	v_mad_u64_u32 v[122:123], s[6:7], v118, s84, 0
	v_mad_i32_i24 v125, v121, s84, v125
	v_mad_i32_i24 v123, v119, s84, v123
	s_mov_b32 s10, 0
	s_mov_b32 s11, 0
	s_waitcnt vmcnt(0) lgkmcnt(0)
	v_pk_mul_f32 v[46:47], v[50:51], v[46:47] op_sel_hi:[0,1]
	v_pk_mul_f32 v[44:45], v[50:51], v[44:45] op_sel_hi:[0,1]
	v_pk_mul_f32 v[42:43], v[50:51], v[42:43] op_sel_hi:[0,1]
	v_pk_mul_f32 v[40:41], v[50:51], v[40:41] op_sel_hi:[0,1]
	v_pk_mul_f32 v[38:39], v[50:51], v[38:39] op_sel_hi:[0,1]
	v_pk_mul_f32 v[36:37], v[50:51], v[36:37] op_sel_hi:[0,1]
	v_pk_mul_f32 v[48:49], v[50:51], v[34:35] op_sel_hi:[0,1]
	v_pk_mul_f32 v[50:51], v[50:51], v[32:33] op_sel_hi:[0,1]
	v_cvt_pk_bf16_f32 v32, v44, v45
	v_cvt_pk_bf16_f32 v33, v46, v47
	v_cvt_pk_bf16_f32 v34, v40, v41
	v_cvt_pk_bf16_f32 v35, v42, v43
	v_cvt_pk_bf16_f32 v36, v36, v37
	v_cvt_pk_bf16_f32 v37, v38, v39
	v_cvt_pk_bf16_f32 v38, v50, v51
	v_cvt_pk_bf16_f32 v39, v48, v49
	ds_write_b128 v173, v[32:35]
	ds_write_b128 v174, v[36:39]
	v_div_scale_f32 v33, s[6:7], v52, v52, 1.0
	v_rcp_f32_e32 v34, v33
	v_div_scale_f32 v35, vcc, 1.0, v52, 1.0
	v_mov_b32_e32 v36, v144
	v_fma_f32 v37, -v33, v34, 1.0
	v_fmac_f32_e32 v34, v37, v34
	v_mul_f32_e32 v37, v35, v34
	v_fma_f32 v38, -v33, v37, v35
	v_fmac_f32_e32 v37, v38, v34
	v_fma_f32 v33, -v33, v37, v35
	v_div_fmas_f32 v33, v33, v34, v37
	v_div_fixup_f32 v33, v33, v52, 1.0
	v_cmp_lt_f32_e32 vcc, 0, v52
	s_nop 1
	v_cndmask_b32_e32 v66, 0, v33, vcc
	v_pk_mul_f32 v[28:29], v[28:29], v[66:67] op_sel_hi:[1,0]
	v_pk_mul_f32 v[30:31], v[30:31], v[66:67] op_sel_hi:[1,0]
	v_pk_mul_f32 v[24:25], v[24:25], v[66:67] op_sel_hi:[1,0]
	v_pk_mul_f32 v[26:27], v[26:27], v[66:67] op_sel_hi:[1,0]
	v_pk_mul_f32 v[20:21], v[20:21], v[66:67] op_sel_hi:[1,0]
	v_pk_mul_f32 v[22:23], v[22:23], v[66:67] op_sel_hi:[1,0]
	v_pk_mul_f32 v[16:17], v[16:17], v[66:67] op_sel_hi:[1,0]
	v_pk_mul_f32 v[18:19], v[18:19], v[66:67] op_sel_hi:[1,0]
	v_mov_b32_e32 v32, v251
	s_waitcnt vmcnt(0) lgkmcnt(0)
	v_pk_mul_f32 v[30:31], v[32:33], v[30:31] op_sel_hi:[0,1]
	v_pk_mul_f32 v[28:29], v[32:33], v[28:29] op_sel_hi:[0,1]
	v_pk_mul_f32 v[26:27], v[32:33], v[26:27] op_sel_hi:[0,1]
	v_pk_mul_f32 v[24:25], v[32:33], v[24:25] op_sel_hi:[0,1]
	v_pk_mul_f32 v[20:21], v[32:33], v[20:21] op_sel_hi:[0,1]
	v_pk_mul_f32 v[22:23], v[32:33], v[22:23] op_sel_hi:[0,1]
	v_pk_mul_f32 v[34:35], v[32:33], v[18:19] op_sel_hi:[0,1]
	v_pk_mul_f32 v[32:33], v[32:33], v[16:17] op_sel_hi:[0,1]
	v_cvt_pk_bf16_f32 v16, v28, v29
	v_cvt_pk_bf16_f32 v17, v30, v31
	v_cvt_pk_bf16_f32 v18, v24, v25
	v_cvt_pk_bf16_f32 v19, v26, v27
	v_cvt_pk_bf16_f32 v20, v20, v21
	v_cvt_pk_bf16_f32 v21, v22, v23
	v_cvt_pk_bf16_f32 v22, v32, v33
	v_cvt_pk_bf16_f32 v23, v34, v35
	ds_write_b128 v175, v[16:19]
	ds_write_b128 v176, v[20:23]
	s_nop 0
	v_ashrrev_i32_e32 v20, 3, v36
	v_ashrrev_i32_e32 v21, 31, v20
	v_lshlrev_b32_e32 v18, 4, v36
	v_lshlrev_b64 v[22:23], 7, v[20:21]
	v_lshl_add_u64 v[16:17], s[14:15], 0, v[22:23]
	v_and_b32_e32 v146, 0x70, v18
	v_lshl_add_u64 v[16:17], v[16:17], 0, v[146:147]
	global_load_dwordx4 v[16:19], v[16:17], off
	v_lshlrev_b32_e32 v26, 7, v20
	v_lshrrev_b32_e32 v20, 1, v20
	v_xor_b32_e32 v20, v20, v36
	v_lshlrev_b32_e32 v20, 4, v20
	v_and_b32_e32 v20, 0x70, v20
	v_lshrrev_b32_e32 v24, 4, v36
	v_bfe_u32 v25, v36, 4, 2
	v_add_u32_e32 v27, 0, v20
	v_bfe_u32 v20, v36, 1, 3
	v_bitop3_b32 v24, v24, v20, 3 bitop3:0x6c
	v_bitop3_b32 v20, v25, v20, 4 bitop3:0x36
	v_lshlrev_b32_e32 v29, 4, v20
	v_and_b32_e32 v20, 7, v36
	v_and_b32_e32 v21, 15, v36
	v_lshl_or_b32 v22, v20, 4, v22
	v_lshl_add_u32 v28, v21, 7, 0
	v_lshlrev_b32_e32 v24, 4, v24
	v_cmp_gt_u32_e32 vcc, 4, v21
	v_lshl_add_u64 v[20:21], s[14:15], 0, v[22:23]
	v_lshlrev_b32_e32 v65, 6, v25
	v_lshl_add_u64 v[68:69], v[20:21], 0, s[38:39]
	v_lshl_add_u32 v67, v25, 2, v182
	v_add_u32_e32 v70, v27, v26
	v_add_u32_e32 v71, v28, v24
	v_add_u32_e32 v72, v28, v29
	v_lshlrev_b32_e32 v52, 4, v144
	v_add_u32_e32 v52, 0x2000, v52
	v_mov_b32_e32 v220, 0
	v_mov_b32_e32 v221, 0
	v_mov_b32_e32 v222, 0
	v_mov_b32_e32 v223, 0
	s_waitcnt lgkmcnt(0)
	s_barrier
	ds_write_b128 v52, v[220:223]
	ds_write_b128 v52, v[220:223] offset:8192
	ds_write_b128 v52, v[220:223] offset:16384
	ds_write_b128 v52, v[220:223] offset:24576
	v_cmp_gt_u32_e64 s[12:13], 64, v144
	s_nop 1
	s_and_saveexec_b64 s[14:15], s[12:13]
	ds_write_b128 v52, v[220:223] offset:32768
	s_or_b64 exec, exec, s[14:15]
	s_branch .LBB0_1020

; __device__ __forceinline__ v4u pack8(const f32x4& a, const f32x4& b) { return (v4u){cvtpk(a[0], a[1]), cvtpk(a[2], a[3]), cvtpk(b[0], b[1]), cvtpk(b[2], b[3])}; }
; __device__ __forceinline__ f32x4 unpk_lo(const v4u& w) { return (f32x4){__uint_as_float(w.x << 16), __uint_as_float(w.x & 0xffff0000u), __uint_as_float(w.y << 16), __uint_as_float(w.y & 0xffff0000u)}; }
; __device__ __forceinline__ f32x4 unpk_hi(const v4u& w) { return (f32x4){__uint_as_float(w.z << 16), __uint_as_float(w.z & 0xffff0000u), __uint_as_float(w.w << 16), __uint_as_float(w.w & 0xffff0000u)}; }
; __device__ __forceinline__ void sel_pass(LAS unsigned char* lds, const bf16* K0, const bf16* V, int thi, const bf16x8 (&qf)[2][2], const int (&tpos)[2], const int (&tok)[2], int wave_tmin, int wave_tmax,
;         f32x4 (&o)[2][4], float (&mfin)[2], float (&linv)[2], int tid, int fr, int fq) {
;     ...
;     for (int i = 0; i < 2; ++i) {
;         const float lt = rows_sum(l[i]);
;         const float iv = lt > 0.f ? 1.0f / lt : 0.f;
;         mfin[i] = m[i]; linv[i] = iv;
; #pragma unroll
;         for (int dt = 0; dt < 4; ++dt) o[i][dt] = o[i][dt] * iv;
;     }
; __device__ __forceinline__ void nsa_item(LAS unsigned char* lds, const NsaPtrs& P, int b, int g, int qb, int tid) {
;     ...
;     for (int i = 0; i < 2; ++i) { const float gs = P.GATES[((size_t)b * T + tpos[i]) * 24 + g * 12 + hh * 3 + 1];
; #pragma unroll
;         for (int h = 0; h < 2; ++h) { const v4u w = ocl[(i * 2 + h) * NTHREADS + tid]; ocl[(i * 2 + h) * NTHREADS + tid] = pack8(unpk_lo(w) + o[i][2 * h] * gs, unpk_hi(w) + o[i][2 * h + 1] * gs); } }
;     ...
;     nsa_load_q(P.QN, b, g, tid, t0, qf);
.LBB0_1189:
	v_mov_b32_e32 v20, v100
	v_mov_b32_e32 v21, v134
	v_mov_b32_e32 v22, v135
	s_nop 0
	v_permlane16_swap_b32_e32 v134, v21
	v_permlane16_swap_b32_e32 v135, v22
	v_add_f32_e32 v23, v134, v21
	v_add_f32_e32 v22, v135, v22
	v_mov_b32_e32 v25, v23
	v_mov_b32_e32 v24, v22
	s_nop 0
	v_permlane32_swap_b32_e32 v23, v25
	v_permlane32_swap_b32_e32 v22, v24
	v_pk_add_f32 v[22:23], v[22:23], v[24:25]
	ds_read_b128 v[12:15], v173
	ds_read_b128 v[16:19], v173 offset:8192
	v_div_scale_f32 v21, s[6:7], v23, v23, 1.0
	s_waitcnt vmcnt(0) lgkmcnt(0)
	v_rcp_f32_e32 v36, v21
	v_div_scale_f32 v37, vcc, 1.0, v23, 1.0
	v_lshlrev_b32_e32 v24, 16, v12
	v_fma_f32 v38, -v21, v36, 1.0
	v_fmac_f32_e32 v36, v38, v36
	v_mul_f32_e32 v38, v37, v36
	v_fma_f32 v39, -v21, v38, v37
	v_fmac_f32_e32 v38, v39, v36
	v_fma_f32 v21, -v21, v38, v37
	v_div_fmas_f32 v21, v21, v36, v38
	v_div_fixup_f32 v21, v21, v23, 1.0
	v_cmp_lt_f32_e32 vcc, 0, v23
	v_and_b32_e32 v25, 0xffff0000, v12
	v_lshlrev_b32_e32 v12, 16, v13
	v_cndmask_b32_e32 v36, 0, v21, vcc
	v_and_b32_e32 v13, 0xffff0000, v13
	v_lshlrev_b32_e32 v26, 16, v14
	v_and_b32_e32 v27, 0xffff0000, v14
	v_lshlrev_b32_e32 v14, 16, v15
	v_and_b32_e32 v15, 0xffff0000, v15
	v_pk_mul_f32 v[38:39], v[60:61], v[36:37] op_sel_hi:[1,0]
	v_pk_mul_f32 v[44:45], v[62:63], v[36:37] op_sel_hi:[1,0]
	v_pk_mul_f32 v[46:47], v[56:57], v[36:37] op_sel_hi:[1,0]
	v_pk_mul_f32 v[48:49], v[58:59], v[36:37] op_sel_hi:[1,0]
	v_lshlrev_b32_e32 v32, 16, v16
	v_and_b32_e32 v33, 0xffff0000, v16
	v_lshlrev_b32_e32 v16, 16, v17
	v_and_b32_e32 v17, 0xffff0000, v17
	v_lshlrev_b32_e32 v34, 16, v18
	v_and_b32_e32 v35, 0xffff0000, v18
	v_lshlrev_b32_e32 v18, 16, v19
	v_and_b32_e32 v19, 0xffff0000, v19
	v_pk_mul_f32 v[50:51], v[52:53], v[36:37] op_sel_hi:[1,0]
	v_pk_mul_f32 v[52:53], v[54:55], v[36:37] op_sel_hi:[1,0]
	v_pk_mul_f32 v[40:41], v[40:41], v[36:37] op_sel_hi:[1,0]
	v_pk_mul_f32 v[36:37], v[42:43], v[36:37] op_sel_hi:[1,0]
	s_add_u32 s6, s54, s50
	s_addc_u32 s11, s55, s51
	s_add_u32 s8, s6, 0xba00000
	s_addc_u32 s9, s11, 0
	s_add_u32 s10, s6, 0xbe00000
	v_mov_b32_e32 v23, s47
	s_addc_u32 s11, s11, 0
	v_pk_fma_f32 v[42:43], v[20:21], v[44:45], v[12:13] op_sel_hi:[0,1,1]
	v_pk_fma_f32 v[12:13], v[20:21], v[38:39], v[24:25] op_sel_hi:[0,1,1]
	v_pk_fma_f32 v[24:25], v[20:21], v[48:49], v[14:15] op_sel_hi:[0,1,1]
	v_pk_fma_f32 v[14:15], v[20:21], v[46:47], v[26:27] op_sel_hi:[0,1,1]
	v_pk_fma_f32 v[26:27], v[20:21], v[52:53], v[16:17] op_sel_hi:[0,1,1]
	v_pk_fma_f32 v[16:17], v[20:21], v[50:51], v[32:33] op_sel_hi:[0,1,1]
	v_pk_fma_f32 v[32:33], v[20:21], v[36:37], v[18:19] op_sel_hi:[0,1,1]
	v_pk_fma_f32 v[18:19], v[20:21], v[40:41], v[34:35] op_sel_hi:[0,1,1]
	v_cvt_pk_bf16_f32 v12, v12, v13
	v_cvt_pk_bf16_f32 v13, v42, v43
	v_cvt_pk_bf16_f32 v14, v14, v15
	v_cvt_pk_bf16_f32 v15, v24, v25
	v_cvt_pk_bf16_f32 v16, v16, v17
	v_cvt_pk_bf16_f32 v17, v26, v27
	v_cvt_pk_bf16_f32 v18, v18, v19
	v_cvt_pk_bf16_f32 v19, v32, v33
	ds_write_b128 v173, v[12:15]
	ds_write_b128 v173, v[16:19] offset:8192
	v_mov_b32_e32 v24, v101
	v_div_scale_f32 v38, s[6:7], v22, v22, 1.0
	v_rcp_f32_e32 v39, v38
	v_div_scale_f32 v40, vcc, 1.0, v22, 1.0
	ds_read_b128 v[14:17], v173 offset:16384
	ds_read_b128 v[18:21], v173 offset:24576
	v_fma_f32 v41, -v38, v39, 1.0
	v_fmac_f32_e32 v39, v41, v39
	v_mul_f32_e32 v41, v40, v39
	v_fma_f32 v42, -v38, v41, v40
	v_fmac_f32_e32 v41, v42, v39
	v_fma_f32 v38, -v38, v41, v40
	v_div_fmas_f32 v38, v38, v39, v41
	v_div_fixup_f32 v38, v38, v22, 1.0
	v_cmp_lt_f32_e32 vcc, 0, v22
	v_sub_u32_e64 v25, s72, 8 clamp
	s_waitcnt lgkmcnt(0)
	v_lshlrev_b32_e32 v26, 16, v14
	v_cndmask_b32_e32 v22, 0, v38, vcc
	v_and_b32_e32 v27, 0xffff0000, v14
	v_lshlrev_b32_e32 v14, 16, v15
	v_and_b32_e32 v15, 0xffff0000, v15
	v_lshlrev_b32_e32 v32, 16, v16
	v_and_b32_e32 v33, 0xffff0000, v16
	v_lshlrev_b32_e32 v16, 16, v17
	v_and_b32_e32 v17, 0xffff0000, v17
	v_pk_mul_f32 v[28:29], v[28:29], v[22:23] op_sel_hi:[1,0]
	v_pk_mul_f32 v[30:31], v[30:31], v[22:23] op_sel_hi:[1,0]
	v_pk_mul_f32 v[8:9], v[8:9], v[22:23] op_sel_hi:[1,0]
	v_pk_mul_f32 v[10:11], v[10:11], v[22:23] op_sel_hi:[1,0]
	v_lshlrev_b32_e32 v34, 16, v18
	v_and_b32_e32 v35, 0xffff0000, v18
	v_lshlrev_b32_e32 v18, 16, v19
	v_and_b32_e32 v19, 0xffff0000, v19
	v_lshlrev_b32_e32 v36, 16, v20
	v_and_b32_e32 v37, 0xffff0000, v20
	v_lshlrev_b32_e32 v20, 16, v21
	v_and_b32_e32 v21, 0xffff0000, v21
	v_pk_mul_f32 v[4:5], v[4:5], v[22:23] op_sel_hi:[1,0]
	v_pk_mul_f32 v[6:7], v[6:7], v[22:23] op_sel_hi:[1,0]
	v_pk_mul_f32 v[0:1], v[0:1], v[22:23] op_sel_hi:[1,0]
	v_pk_mul_f32 v[2:3], v[2:3], v[22:23] op_sel_hi:[1,0]
	v_mov_b32_e32 v13, v144
	v_mov_b32_e32 v12, v144
	v_cmp_gt_u32_e64 s[6:7], s72, v25
	s_waitcnt vmcnt(0)
	v_pk_fma_f32 v[14:15], v[24:25], v[30:31], v[14:15] op_sel_hi:[0,1,1]
	v_pk_fma_f32 v[26:27], v[24:25], v[28:29], v[26:27] op_sel_hi:[0,1,1]
	v_pk_fma_f32 v[10:11], v[24:25], v[10:11], v[16:17] op_sel_hi:[0,1,1]
	v_pk_fma_f32 v[8:9], v[24:25], v[8:9], v[32:33] op_sel_hi:[0,1,1]
	v_pk_fma_f32 v[6:7], v[24:25], v[6:7], v[18:19] op_sel_hi:[0,1,1]
	v_pk_fma_f32 v[4:5], v[24:25], v[4:5], v[34:35] op_sel_hi:[0,1,1]
	v_pk_fma_f32 v[16:17], v[24:25], v[2:3], v[20:21] op_sel_hi:[0,1,1]
	v_pk_fma_f32 v[18:19], v[24:25], v[0:1], v[36:37] op_sel_hi:[0,1,1]
	v_cvt_pk_bf16_f32 v0, v26, v27
	v_cvt_pk_bf16_f32 v1, v14, v15
	v_cvt_pk_bf16_f32 v2, v8, v9
	v_cvt_pk_bf16_f32 v3, v10, v11
	v_cvt_pk_bf16_f32 v4, v4, v5
	v_cvt_pk_bf16_f32 v5, v6, v7
	v_cvt_pk_bf16_f32 v6, v18, v19
	v_cvt_pk_bf16_f32 v7, v16, v17
	ds_write_b128 v173, v[0:3] offset:16384
	ds_write_b128 v173, v[4:7] offset:24576
	s_nop 0
	v_lshlrev_b32_e32 v1, 4, v13
	v_ashrrev_i32_e32 v0, 3, v13
	v_and_b32_e32 v2, 0xc0, v1
	v_and_b32_e32 v0, -8, v0
	v_or_b32_e32 v2, s70, v2
	v_and_or_b32 v22, v13, 3, s86
	v_ashrrev_i32_e32 v1, 31, v0
	v_lshlrev_b32_e32 v146, 1, v2
	v_lshl_add_u64 v[0:1], v[22:23], 0, v[0:1]
	v_lshl_add_u64 v[2:3], s[58:59], 0, v[146:147]
	v_and_b32_e32 v146, 48, v13
	v_lshlrev_b64 v[0:1], 10, v[0:1]
	v_lshl_add_u64 v[2:3], v[2:3], 0, v[146:147]
	v_lshl_add_u64 v[0:1], v[2:3], 0, v[0:1]
	global_load_dwordx4 v[32:35], v[0:1], off
	global_load_dwordx4 v[36:39], v[0:1], off offset:64
	v_add_co_u32_e32 v0, vcc, s75, v0
	s_nop 1
	v_addc_co_u32_e32 v1, vcc, 0, v1, vcc
	global_load_dwordx4 v[40:43], v[0:1], off
	global_load_dwordx4 v[44:47], v[0:1], off offset:64
	v_cmp_le_u32_e32 vcc, s72, v25
	v_ashrrev_i32_e32 v8, 3, v12
	v_lshlrev_b32_e32 v1, 3, v12
	v_lshl_add_u32 v0, v25, 6, v8
	v_and_b32_e32 v4, 56, v1
	v_ashrrev_i32_e32 v1, 31, v0
	v_lshlrev_b64 v[2:3], 7, v[0:1]
	v_lshl_add_u64 v[0:1], s[8:9], 0, v[2:3]
	v_lshlrev_b32_e32 v146, 1, v4
	v_lshl_add_u64 v[0:1], v[0:1], 0, v[146:147]
	global_load_dwordx4 v[48:51], v[0:1], off
	v_lshl_add_u64 v[0:1], s[10:11], 0, v[2:3]
	v_lshl_add_u64 v[0:1], v[0:1], 0, v[146:147]
	global_load_dwordx4 v[52:55], v[0:1], off
	v_readfirstlane_b32 s20, v12
	s_cbranch_vccnz .LBB0_1191
; template <int DQK> __device__ __forceinline__ void stage_load(Stage<DQK>& s, const bf16* K0, int p0, const bf16* K1, int p1, const bf16* V, int pv, int tile, bool withV, int tid) {
;     { const int key = tid >> 3, c = tid & 7; s.k0 = *(const v4u*)(K0 + (size_t)(64 * tile + key) * p0 + 8 * c); }
;     if (DQK == 96) { if (tid < 256) { const int key = tid >> 2, c = tid & 3; s.k1 = *(const v4u*)(K1 + (size_t)(64 * tile + key) * p1 + 8 * c); } }
;     if (withV) { const int key = tid >> 3, c = tid & 7; s.v = *(const v4u*)(V + (size_t)(64 * tile + key) * pv + 8 * c); }
; template <int DQK, int MODE> __device__ __forceinline__ void attn_pass(LAS unsigned char* lds, const bf16* K0, int p0, const bf16* K1, int p1, const bf16* V, int pv, int tlo, int thi, ...
;     ...
;         stage_load<DQK>(st, K0, p0, K1, p1, V, pv, tlo, true, tid);
;         if (tlo < thi) stage_load<DQK>(st1, K0, p0, K1, p1, V, pv, tlo + 1, true, tid);
	v_lshl_add_u64 v[0:1], v[2:3], 0, s[38:39]
	v_lshl_add_u64 v[2:3], s[10:11], 0, v[0:1]
	v_lshl_add_u64 v[0:1], s[8:9], 0, v[0:1]
	v_lshl_add_u64 v[2:3], v[2:3], 0, v[146:147]
	v_lshl_add_u64 v[0:1], v[0:1], 0, v[146:147]
	global_load_dwordx4 v[4:7], v[0:1], off
	s_nop 0
	global_load_dwordx4 v[0:3], v[2:3], off
